# v112 plus fox_attn epilogue o_norm gain loads issued before the unit's closing barrier (latency hidden behind the 1/l scaling and LDS transpose)
# speedup vs baseline: 1.0119x; 1.0119x over previous
.LBB0_161:
	s_or_b64 exec, exec, s[20:21]
	ds_bpermute_b32 v0, v187, v202
	s_lshl_b64 s[2:3], s[34:35], 2
	s_add_u32 s2, s48, s2
	s_mulk_i32 s54, 0x1200
	s_addc_u32 s3, s49, s3
	v_lshlrev_b32_e32 v72, 3, v185
	s_lshl_b32 s20, s57, 2
	v_and_b32_e32 v72, 56, v72
	s_add_u32 s20, s2, s20
	v_lshlrev_b32_e32 v72, 2, v72
	s_addc_u32 s21, s3, 0
	global_load_dwordx4 v[64:67], v72, s[20:21]
	global_load_dwordx4 v[68:71], v72, s[20:21] offset:16
	s_waitcnt lgkmcnt(0)
	v_add_f32_e32 v0, v202, v0
	v_div_scale_f32 v2, s[6:7], v0, v0, 1.0
	v_rcp_f32_e32 v3, v2
	s_add_i32 s6, s54, 0
	s_barrier
	v_fma_f32 v4, -v2, v3, 1.0
	v_fmac_f32_e32 v3, v4, v3
	v_div_scale_f32 v4, vcc, 1.0, v0, 1.0
	v_mul_f32_e32 v5, v4, v3
	v_fma_f32 v6, -v2, v5, v4
	v_fmac_f32_e32 v5, v6, v3
	v_fma_f32 v2, -v2, v5, v4
	v_div_fmas_f32 v2, v2, v3, v5
	v_div_fixup_f32 v0, v2, v0, 1.0
	v_pk_mul_f32 v[2:3], v[34:35], v[0:1] op_sel_hi:[1,0]
	v_pk_mul_f32 v[4:5], v[18:19], v[0:1] op_sel_hi:[1,0]
	v_pk_mul_f32 v[6:7], v[36:37], v[0:1] op_sel_hi:[1,0]
	v_pk_mul_f32 v[8:9], v[20:21], v[0:1] op_sel_hi:[1,0]
	v_pk_mul_f32 v[10:11], v[38:39], v[0:1] op_sel_hi:[1,0]
	v_pk_mul_f32 v[12:13], v[22:23], v[0:1] op_sel_hi:[1,0]
	v_pk_mul_f32 v[14:15], v[40:41], v[0:1] op_sel_hi:[1,0]
	v_pk_mul_f32 v[16:17], v[24:25], v[0:1] op_sel_hi:[1,0]
	v_pk_mul_f32 v[18:19], v[42:43], v[0:1] op_sel_hi:[1,0]
	v_pk_mul_f32 v[20:21], v[26:27], v[0:1] op_sel_hi:[1,0]
	v_pk_mul_f32 v[22:23], v[44:45], v[0:1] op_sel_hi:[1,0]
	v_pk_mul_f32 v[24:25], v[28:29], v[0:1] op_sel_hi:[1,0]
	v_pk_mul_f32 v[26:27], v[46:47], v[0:1] op_sel_hi:[1,0]
	v_pk_mul_f32 v[28:29], v[30:31], v[0:1] op_sel_hi:[1,0]
	v_pk_mul_f32 v[30:31], v[48:49], v[0:1] op_sel_hi:[1,0]
	v_pk_mul_f32 v[32:33], v[32:33], v[0:1] op_sel_hi:[1,0]
	v_mul_u32_u24_e32 v0, 0x90, v188
	v_add3_u32 v0, s6, v0, v191
	v_cvt_pk_bf16_f32 v2, v2, v3
	v_cvt_pk_bf16_f32 v3, v6, v7
	v_cvt_pk_bf16_f32 v6, v10, v11
	v_cvt_pk_bf16_f32 v7, v14, v15
	v_add_u32_e32 v0, 0x8000, v0
	ds_write2_b64 v0, v[2:3], v[6:7] offset1:2
	v_cvt_pk_bf16_f32 v2, v18, v19
	v_cvt_pk_bf16_f32 v3, v22, v23
	v_cvt_pk_bf16_f32 v6, v26, v27
	v_cvt_pk_bf16_f32 v7, v30, v31
	ds_write2_b64 v0, v[2:3], v[6:7] offset0:4 offset1:6
	v_cvt_pk_bf16_f32 v2, v4, v5
	v_cvt_pk_bf16_f32 v3, v8, v9
	v_cvt_pk_bf16_f32 v4, v12, v13
	v_cvt_pk_bf16_f32 v5, v16, v17
	ds_write2_b64 v0, v[2:3], v[4:5] offset0:8 offset1:10
	v_cvt_pk_bf16_f32 v2, v20, v21
	v_cvt_pk_bf16_f32 v3, v24, v25
	v_cvt_pk_bf16_f32 v4, v28, v29
	v_cvt_pk_bf16_f32 v5, v32, v33
	ds_write2_b64 v0, v[2:3], v[4:5] offset0:12 offset1:14
	v_lshlrev_b32_e32 v0, 3, v185
	v_lshrrev_b32_e32 v15, 3, v185
	v_and_b32_e32 v2, 56, v0
	s_lshl_b32 s7, s57, 2
	v_lshlrev_b32_e32 v0, 1, v2
	s_add_u32 s20, s2, s7
	v_lshlrev_b32_e32 v22, 2, v2
	v_mul_u32_u24_e32 v2, 0x90, v15
	s_waitcnt lgkmcnt(0)
	s_addc_u32 s21, s3, 0
	v_add3_u32 v14, s6, v0, v2
	ds_read_b128 v[2:5], v14 offset:32768
	ds_read_b128 v[10:13], v14 offset:33920
	s_mov_b32 s2, 0x358637bd
	s_waitcnt lgkmcnt(0)
	v_lshlrev_b32_e32 v32, 16, v2
	v_and_b32_e32 v33, 0xffff0000, v2
	v_lshlrev_b32_e32 v44, 16, v10
	v_and_b32_e32 v45, 0xffff0000, v10
	v_lshlrev_b32_e32 v28, 16, v3
	v_and_b32_e32 v29, 0xffff0000, v3
	v_pk_mul_f32 v[2:3], v[32:33], v[32:33]
	v_lshlrev_b32_e32 v40, 16, v11
	v_and_b32_e32 v41, 0xffff0000, v11
	v_pk_mul_f32 v[10:11], v[44:45], v[44:45]
	v_pk_mul_f32 v[30:31], v[28:29], v[28:29]
	v_pk_mul_f32 v[42:43], v[40:41], v[40:41]
	v_mov_b32_e32 v46, v10
	v_mov_b32_e32 v47, v2
	v_mov_b32_e32 v2, v11
	v_lshlrev_b32_e32 v26, 16, v4
	v_and_b32_e32 v27, 0xffff0000, v4
	v_lshlrev_b32_e32 v38, 16, v12
	v_and_b32_e32 v39, 0xffff0000, v12
	v_pk_add_f32 v[2:3], v[46:47], v[2:3]
	v_mov_b32_e32 v10, v42
	v_mov_b32_e32 v11, v30
	v_lshlrev_b32_e32 v20, 16, v5
	v_and_b32_e32 v21, 0xffff0000, v5
	v_pk_mul_f32 v[4:5], v[26:27], v[26:27]
	v_lshlrev_b32_e32 v34, 16, v13
	v_and_b32_e32 v35, 0xffff0000, v13
	v_pk_mul_f32 v[12:13], v[38:39], v[38:39]
	v_pk_add_f32 v[2:3], v[10:11], v[2:3]
	v_mov_b32_e32 v30, v43
	v_pk_add_f32 v[2:3], v[30:31], v[2:3]
	v_mov_b32_e32 v10, v12
	v_mov_b32_e32 v11, v4
	v_pk_mul_f32 v[24:25], v[20:21], v[20:21]
	v_pk_mul_f32 v[36:37], v[34:35], v[34:35]
	v_pk_add_f32 v[2:3], v[10:11], v[2:3]
	v_mov_b32_e32 v4, v13
	v_pk_add_f32 v[2:3], v[4:5], v[2:3]
	v_mov_b32_e32 v4, v36
	v_mov_b32_e32 v5, v24
	v_pk_add_f32 v[2:3], v[4:5], v[2:3]
	v_mov_b32_e32 v24, v37
	v_pk_add_f32 v[2:3], v[24:25], v[2:3]
	v_mov_b64_e32 v[12:13], s[2:3]
	s_mov_b32 s2, 0x3c800000
	v_or_b32_e32 v10, s55, v15
	v_mov_b32_e32 v11, s56
	s_waitcnt lgkmcnt(0)
	s_nop 1
	v_add_f32_dpp v2, v2, v2 quad_perm:[1,0,3,2] row_mask:0xf bank_mask:0xf
	v_add_f32_dpp v3, v3, v3 quad_perm:[1,0,3,2] row_mask:0xf bank_mask:0xf
	v_lshlrev_b64 v[24:25], 11, v[10:11]
	s_waitcnt lgkmcnt(0)
	s_nop 1
	v_add_f32_dpp v2, v2, v2 quad_perm:[2,3,0,1] row_mask:0xf bank_mask:0xf
	v_add_f32_dpp v3, v3, v3 quad_perm:[2,3,0,1] row_mask:0xf bank_mask:0xf
	s_waitcnt lgkmcnt(0)
	s_nop 1
	v_add_f32_dpp v2, v2, v2 row_half_mirror row_mask:0xf bank_mask:0xf
	v_add_f32_dpp v3, v3, v3 row_half_mirror row_mask:0xf bank_mask:0xf
	s_nop 0
	v_pk_fma_f32 v[30:31], v[2:3], s[2:3], v[12:13] op_sel_hi:[1,0,0]
	s_nop 0
	v_mul_f32_e32 v2, 0x4b800000, v31
	v_cmp_gt_f32_e32 vcc, s96, v31
	v_mul_f32_e32 v15, 0x4b800000, v30
	s_nop 0
	v_cndmask_b32_e32 v2, v31, v2, vcc
	v_rsq_f32_e32 v4, v2
	v_lshl_add_u64 v[2:3], s[74:75], 0, v[24:25]
	v_lshl_add_u64 v[2:3], v[2:3], 0, s[80:81]
	v_lshl_add_u64 v[24:25], v[2:3], 0, v[0:1]
	v_mul_f32_e32 v2, 0x45800000, v4
	v_cndmask_b32_e32 v2, v4, v2, vcc
	v_pk_mul_f32 v[4:5], v[2:3], v[32:33] op_sel_hi:[0,1]
	s_waitcnt vmcnt(0)
	v_pk_mul_f32 v[4:5], v[64:65], v[4:5]
	v_pk_mul_f32 v[6:7], v[2:3], v[28:29] op_sel_hi:[0,1]
	v_pk_mul_f32 v[6:7], v[66:67], v[6:7]
	v_pk_mul_f32 v[8:9], v[2:3], v[26:27] op_sel_hi:[0,1]
	v_pk_mul_f32 v[2:3], v[2:3], v[20:21] op_sel_hi:[0,1]
	v_pk_mul_f32 v[8:9], v[68:69], v[8:9]
	v_pk_mul_f32 v[16:17], v[70:71], v[2:3]
	v_cvt_pk_bf16_f32 v2, v4, v5
	v_cvt_pk_bf16_f32 v3, v6, v7
	v_cvt_pk_bf16_f32 v4, v8, v9
	v_cvt_pk_bf16_f32 v5, v16, v17
	global_store_dwordx4 v[24:25], v[2:5], off offset:512
	s_nop 0
	v_cmp_gt_f32_e32 vcc, s96, v30
	v_mov_b32_e32 v17, s56
	v_or_b32_e32 v16, 8, v10
	v_cndmask_b32_e32 v15, v30, v15, vcc
	v_rsq_f32_e32 v15, v15
	v_lshlrev_b64 v[16:17], 11, v[16:17]
	v_lshl_add_u64 v[16:17], s[74:75], 0, v[16:17]
	v_lshl_add_u64 v[16:17], v[16:17], 0, s[80:81]
	v_mul_f32_e32 v23, 0x45800000, v15
	v_cndmask_b32_e32 v24, v15, v23, vcc
	v_pk_mul_f32 v[26:27], v[24:25], v[44:45] op_sel_hi:[0,1]
	v_pk_mul_f32 v[28:29], v[24:25], v[40:41] op_sel_hi:[0,1]
	v_pk_mul_f32 v[30:31], v[24:25], v[38:39] op_sel_hi:[0,1]
	v_pk_mul_f32 v[24:25], v[24:25], v[34:35] op_sel_hi:[0,1]
	v_lshl_add_u64 v[20:21], v[16:17], 0, v[0:1]
	ds_read_b128 v[16:19], v14 offset:35072
	s_waitcnt lgkmcnt(0)
	v_lshlrev_b32_e32 v34, 16, v16
	v_and_b32_e32 v35, 0xffff0000, v16
	v_lshlrev_b32_e32 v32, 16, v17
	v_and_b32_e32 v33, 0xffff0000, v17
	v_pk_mul_f32 v[38:39], v[34:35], v[34:35]
	v_pk_mul_f32 v[36:37], v[32:33], v[32:33]
	v_mov_b32_e32 v49, v38
	v_pk_mul_f32 v[2:3], v[64:65], v[26:27]
	v_pk_mul_f32 v[4:5], v[66:67], v[28:29]
	v_pk_mul_f32 v[6:7], v[68:69], v[30:31]
	v_pk_mul_f32 v[8:9], v[70:71], v[24:25]
	v_cvt_pk_bf16_f32 v2, v2, v3
	v_cvt_pk_bf16_f32 v3, v4, v5
	v_cvt_pk_bf16_f32 v4, v6, v7
	v_cvt_pk_bf16_f32 v5, v8, v9
	global_store_dwordx4 v[20:21], v[2:5], off offset:512
	s_nop 0
	ds_read_b128 v[24:27], v14 offset:36224
	v_lshlrev_b32_e32 v28, 16, v19
	v_and_b32_e32 v29, 0xffff0000, v19
	v_lshlrev_b32_e32 v30, 16, v18
	v_and_b32_e32 v31, 0xffff0000, v18
	s_waitcnt lgkmcnt(0)
	v_lshlrev_b32_e32 v20, 16, v24
	v_and_b32_e32 v21, 0xffff0000, v24
	v_lshlrev_b32_e32 v18, 16, v25
	v_and_b32_e32 v19, 0xffff0000, v25
	v_pk_mul_f32 v[46:47], v[20:21], v[20:21]
	v_pk_mul_f32 v[44:45], v[18:19], v[18:19]
	v_mov_b32_e32 v48, v46
	v_mov_b32_e32 v38, v47
	v_lshlrev_b32_e32 v16, 16, v26
	v_and_b32_e32 v17, 0xffff0000, v26
	v_mov_b32_e32 v46, v44
	v_mov_b32_e32 v47, v36
	v_pk_add_f32 v[38:39], v[48:49], v[38:39]
	v_lshlrev_b32_e32 v14, 16, v27
	v_and_b32_e32 v15, 0xffff0000, v27
	v_pk_mul_f32 v[26:27], v[30:31], v[30:31]
	v_pk_mul_f32 v[42:43], v[16:17], v[16:17]
	v_mov_b32_e32 v36, v45
	v_pk_add_f32 v[38:39], v[46:47], v[38:39]
	v_mov_b32_e32 v44, v42
	v_mov_b32_e32 v45, v26
	v_pk_add_f32 v[36:37], v[36:37], v[38:39]
	v_pk_mul_f32 v[24:25], v[28:29], v[28:29]
	v_pk_mul_f32 v[40:41], v[14:15], v[14:15]
	v_mov_b32_e32 v26, v43
	v_pk_add_f32 v[36:37], v[44:45], v[36:37]
	v_mov_b32_e32 v42, v40
	v_mov_b32_e32 v43, v24
	v_pk_add_f32 v[26:27], v[26:27], v[36:37]
	v_mov_b32_e32 v24, v41
	v_pk_add_f32 v[26:27], v[42:43], v[26:27]
	v_mov_b32_e32 v37, s56
	v_pk_add_f32 v[24:25], v[24:25], v[26:27]
	v_or_b32_e32 v36, 16, v10
	v_lshlrev_b64 v[36:37], 11, v[36:37]
	v_or_b32_e32 v10, 24, v10
	v_lshlrev_b64 v[10:11], 11, v[10:11]
	s_waitcnt lgkmcnt(0)
	s_nop 1
	v_add_f32_dpp v24, v24, v24 quad_perm:[1,0,3,2] row_mask:0xf bank_mask:0xf
	v_add_f32_dpp v25, v25, v25 quad_perm:[1,0,3,2] row_mask:0xf bank_mask:0xf
	v_lshl_add_u64 v[10:11], s[74:75], 0, v[10:11]
	v_lshl_add_u64 v[10:11], v[10:11], 0, s[80:81]
	s_waitcnt lgkmcnt(0)
	s_nop 1
	v_add_f32_dpp v24, v24, v24 quad_perm:[2,3,0,1] row_mask:0xf bank_mask:0xf
	v_add_f32_dpp v25, v25, v25 quad_perm:[2,3,0,1] row_mask:0xf bank_mask:0xf
	s_waitcnt lgkmcnt(0)
	s_nop 1
	v_add_f32_dpp v24, v24, v24 row_half_mirror row_mask:0xf bank_mask:0xf
	v_add_f32_dpp v25, v25, v25 row_half_mirror row_mask:0xf bank_mask:0xf
	s_nop 0
	v_pk_fma_f32 v[12:13], v[24:25], s[2:3], v[12:13] op_sel_hi:[1,0,0]
	v_lshl_add_u64 v[24:25], s[74:75], 0, v[36:37]
	v_mul_f32_e32 v23, 0x4b800000, v13
	v_cmp_gt_f32_e32 vcc, s96, v13
	v_lshl_add_u64 v[24:25], v[24:25], 0, s[80:81]
	v_lshl_add_u64 v[24:25], v[24:25], 0, v[0:1]
	v_cndmask_b32_e32 v13, v13, v23, vcc
	v_rsq_f32_e32 v13, v13
	s_nop 0
	v_mul_f32_e32 v23, 0x45800000, v13
	v_cndmask_b32_e32 v26, v13, v23, vcc
	v_pk_mul_f32 v[34:35], v[26:27], v[34:35] op_sel_hi:[0,1]
	v_pk_mul_f32 v[32:33], v[26:27], v[32:33] op_sel_hi:[0,1]
	v_pk_mul_f32 v[30:31], v[26:27], v[30:31] op_sel_hi:[0,1]
	v_pk_mul_f32 v[26:27], v[26:27], v[28:29] op_sel_hi:[0,1]
	v_mul_f32_e32 v13, 0x4b800000, v12
	v_cmp_gt_f32_e32 vcc, s96, v12
	v_pk_mul_f32 v[28:29], v[68:69], v[30:31]
	v_pk_mul_f32 v[6:7], v[64:65], v[34:35]
	v_pk_mul_f32 v[8:9], v[66:67], v[32:33]
	v_pk_mul_f32 v[26:27], v[70:71], v[26:27]
	v_cvt_pk_bf16_f32 v2, v6, v7
	v_cvt_pk_bf16_f32 v3, v8, v9
	v_cvt_pk_bf16_f32 v4, v28, v29
	v_cvt_pk_bf16_f32 v5, v26, v27
	global_store_dwordx4 v[24:25], v[2:5], off offset:512
	s_nop 0
	v_cndmask_b32_e32 v12, v12, v13, vcc
	v_rsq_f32_e32 v12, v12
	s_nop 0
	v_mul_f32_e32 v13, 0x45800000, v12
	v_cndmask_b32_e32 v12, v12, v13, vcc
	v_pk_mul_f32 v[20:21], v[12:13], v[20:21] op_sel_hi:[0,1]
	v_pk_mul_f32 v[18:19], v[12:13], v[18:19] op_sel_hi:[0,1]
	v_pk_mul_f32 v[16:17], v[12:13], v[16:17] op_sel_hi:[0,1]
	v_pk_mul_f32 v[12:13], v[12:13], v[14:15] op_sel_hi:[0,1]
	v_pk_mul_f32 v[2:3], v[64:65], v[20:21]
	v_pk_mul_f32 v[4:5], v[66:67], v[18:19]
	v_pk_mul_f32 v[6:7], v[68:69], v[16:17]
	v_pk_mul_f32 v[8:9], v[70:71], v[12:13]
	v_cvt_pk_bf16_f32 v2, v2, v3
	v_cvt_pk_bf16_f32 v3, v4, v5
	v_cvt_pk_bf16_f32 v4, v6, v7
	v_cvt_pk_bf16_f32 v5, v8, v9
	v_lshl_add_u64 v[6:7], v[10:11], 0, v[0:1]
	global_store_dwordx4 v[6:7], v[2:5], off offset:512
